# v3 plus GLA pass B: gla_norm_g loads hoisted out of the chunk loop, four per-token sum-of-squares shuffles batched (2 LDS round trips instead of 8)
# speedup vs baseline: 1.0119x; 1.0081x over previous
; #define LAS __attribute__((address_space(3)))
; __device__ __forceinline__ int opaque_tid() { int t = threadIdx.x; asm volatile("" : "+v"(t)); return t; }
; template <bool FULL>
; __device__ __forceinline__ void gla_pass(const Params& P, LAS unsigned char* lds, f32x4 (&S)[8][2], int bh, int c0, int L, bool dry) {
;     ...
;     const int tid = opaque_tid(), lane = tid & 63, w = tid >> 6, fr = lane & 15, g = lane >> 4;
;     bf16_t* PJ = (bf16_t*)(P.ws + WS_PJ); const float* DEC = (const float*)(P.ws + WS_DEC); const bf16_t* PB = (const bf16_t*)(P.ws + WS_PB);
;     LAS unsigned char* Lks = lds + O_KS; LAS unsigned char* Lqd = lds + O_QD; LAS unsigned char* Lv = lds + O_V; LAS unsigned char* Lp = lds + O_P; LAS unsigned char* Lst = lds + O_ST;
;     LAS float* red = (LAS float*)(lds + O_RED); LAS float* Ldec = (LAS float*)(lds + O_DEC);
;     const int b = bh >> 2, h = bh & 3;
;     u32x4 rk[2], rq[2], rv[4], rp; f32x4 rd = (f32x4){0.f, 0.f, 0.f, 0.f};
;     const unsigned gk = (unsigned)(tid * 16), gv = (unsigned)(tid * 16);
;     const unsigned lk = (unsigned)((tid >> 4) * KS_P + 16 * (tid & 15)), lq = (unsigned)((tid >> 4) * QD_P + 16 * (tid & 15)), lv = (unsigned)((tid >> 5) * V_P + 16 * (tid & 31)), lp = (unsigned)((tid >> 3) * P_P + 16 * (tid & 7));
;     ...
;     GLA_LOAD(c0); GLA_STORE();
;     __syncthreads();
;     ...
;             for (int vt = 0; vt < 2; ++vt) gn[vt] = *(const f32x4*)(P.gla_norm_g + 32 * w + 4 * g + 16 * vt);
.LBB0_694:
	s_or_b64 exec, exec, s[6:7]
	v_lshrrev_b32_e32 v112, 3, v108
	s_movk_i32 s6, 0x90
	v_lshrrev_b32_e32 v107, 4, v108
	v_mul_lo_u32 v112, v112, s6
	s_movk_i32 s6, 0x120
	v_mul_lo_u32 v107, v107, s6
	v_and_b32_e32 v109, 0xf0, v152
	v_lshrrev_b32_e32 v110, 5, v108
	s_movk_i32 s6, 0x220
	v_add_u32_e32 v107, 0, v107
	v_and_b32_e32 v114, -16, v108
	v_mul_lo_u32 v110, v110, s6
	v_add_u32_e32 v182, v107, v109
	v_sub_u32_e32 v107, v107, v114
	v_and_b32_e32 v111, 0x1f0, v152
	v_add_u32_e32 v183, v107, v109
	v_add_u32_e32 v107, 0, v110
	s_add_i32 s17, 0, 0x11400
	v_and_b32_e32 v113, 0x70, v152
	v_add_u32_e32 v184, v107, v111
	v_add_u32_e32 v107, s17, v112
	v_add_u32_e32 v185, v107, v113
	v_add_u32_e32 v186, 0, v152
	s_waitcnt vmcnt(8)
	ds_write_b128 v182, v[64:67]
	s_waitcnt vmcnt(7)
	ds_write_b128 v183, v[68:71] offset:18432
	s_waitcnt vmcnt(3)
	ds_write_b128 v182, v[76:79] offset:9216
	ds_write_b128 v183, v[72:75] offset:27136
	ds_write_b128 v184, v[80:83] offset:35840
	ds_write_b128 v184, v[84:87] offset:44544
	s_waitcnt vmcnt(2)
	ds_write_b128 v184, v[92:95] offset:53248
	s_waitcnt vmcnt(1)
	ds_write_b128 v184, v[96:99] offset:61952
	s_waitcnt vmcnt(0)
	ds_write_b128 v185, v[100:103]
	s_and_saveexec_b64 s[6:7], s[4:5]
	v_add_u32_e32 v107, 0x25000, v186
	ds_write_b128 v107, v[88:91]
	s_or_b64 exec, exec, s[6:7]
	v_ashrrev_i32_e32 v107, 6, v108
	v_lshlrev_b32_e32 v110, 5, v107
	v_ashrrev_i32_e32 v111, 31, v110
	v_bfe_u32 v109, v108, 4, 2
	v_lshlrev_b64 v[112:113], 1, v[110:111]
	s_lshl_b32 s6, s1, 10
	v_lshl_add_u64 v[114:115], s[70:71], 0, v[112:113]
	v_lshlrev_b32_e32 v160, 3, v109
	v_mov_b32_e32 v161, 0
	v_mbcnt_hi_u32_b32 v123, -1, v195
	s_lshl_b32 s1, s1, 9
	s_add_i32 s11, s0, 16
	s_and_b32 s25, s6, 0x7000
	v_lshl_add_u64 v[114:115], v[114:115], 0, v[160:161]
	v_and_b32_e32 v125, 64, v123
	s_add_i32 s27, 0, 0x24800
	s_mov_b64 s[18:19], 0x12000020
	s_and_b32 s1, s1, 0x600
	v_and_b32_e32 v116, 15, v108
	v_and_b32_e32 v117, 0xffffffc0, v108
	v_bfe_u32 v108, v108, 2, 2
	v_xor_b32_e32 v124, 16, v123
	v_add_u32_e32 v125, 64, v125
	v_lshl_add_u64 v[164:165], v[114:115], 0, s[18:19]
	s_add_u32 s18, s68, s1
	s_mov_b64 s[6:7], 0x12000000
	v_or_b32_e32 v118, v160, v108
	v_and_b32_e32 v108, 24, v104
	v_cmp_lt_i32_e32 vcc, v124, v125
	s_addc_u32 s19, s69, 0
	s_lshl_b64 s[14:15], s[14:15], 9
	v_lshl_add_u64 v[162:163], v[114:115], 0, s[6:7]
	v_add_u32_e32 v119, 0, v108
	v_or_b32_e32 v108, v110, v116
	s_movk_i32 s6, 0x110
	v_cndmask_b32_e32 v124, v123, v124, vcc
	s_add_u32 s14, s70, s14
	v_mul_lo_u32 v120, v108, s6
	v_lshlrev_b32_e32 v108, 4, v109
	v_lshlrev_b32_e32 v188, 2, v124
	v_xor_b32_e32 v124, 32, v123
	v_cmp_eq_u32_e64 s[6:7], 0, v109
	v_lshlrev_b32_e32 v109, 5, v116
	s_addc_u32 s15, s71, s15
	v_cmp_lt_i32_e32 vcc, v124, v125
	v_add_u32_e32 v190, s27, v109
	s_add_u32 s8, s70, s8
	v_cndmask_b32_e32 v123, v123, v124, vcc
	v_lshl_add_u32 v191, v107, 2, v190
	v_ashrrev_i32_e32 v107, 31, v106
	v_or_b32_e32 v125, 0x200, v109
	v_or_b32_e32 v126, 0x400, v109
	v_or_b32_e32 v127, 0x600, v109
	v_lshl_add_u64 v[110:111], v[110:111], 2, s[58:59]
	v_mov_b32_e32 v109, v161
	s_addc_u32 s9, s71, s9
	v_add_u32_e32 v117, v119, v117
	v_add_u32_e32 v121, s12, v120
	v_add_u32_e32 v187, 0, v108
	v_add_u32_e32 v122, s17, v108
	v_lshlrev_b32_e32 v189, 2, v123
	v_add_u32_e32 v123, s12, v160
	v_mul_u32_u24_e32 v114, 0x220, v118
	v_mul_u32_u24_e32 v115, 0x110, v116
	v_mul_u32_u24_e32 v124, 0x90, v116
	v_mul_u32_u24_e32 v118, 0x120, v118
	v_lshl_add_u64 v[166:167], v[110:111], 0, v[108:109]
	global_load_dwordx4 v[238:241], v[166:167], off
	global_load_dwordx4 v[242:245], v[166:167], off offset:64
	v_lshl_add_u64 v[110:111], s[18:19], 0, v[112:113]
	v_lshl_add_u64 v[106:107], v[106:107], 2, s[14:15]
	s_mov_b64 s[14:15], 0x1a00200
	v_lshl_add_u64 v[104:105], v[104:105], 1, s[8:9]
	s_mov_b64 s[8:9], 0x1e002000
	s_add_i32 s25, s25, s16
	v_mov_b32_e32 v155, v153
	v_mov_b32_e32 v157, v153
	v_mov_b32_e32 v159, v153
	s_mov_b32 s13, 0
	v_lshl_add_u64 v[168:169], v[110:111], 0, v[160:161]
	v_lshl_add_u64 v[170:171], v[106:107], 0, s[14:15]
	v_lshl_add_u64 v[172:173], v[104:105], 0, s[8:9]
	s_add_i32 s0, s0, 1
	v_add_u32_e32 v192, s10, v116
	v_add_u32_e32 v193, s25, v116
	v_add_u32_e32 v196, v117, v114
	v_add_u32_e32 v197, v121, v108
	v_add_u32_e32 v198, v187, v115
	v_add_u32_e32 v199, v122, v124
	v_add_u32_e32 v200, v119, v118
	s_movk_i32 s1, 0x7fff
	s_mov_b32 s25, 0xffff0000
	v_add_u32_e32 v201, v123, v120
	v_mov_b32_e32 v202, 0x358637bd
	s_mov_b32 s26, 0xf800000
	v_mov_b32_e32 v203, 0x260
	s_mov_b64 s[14:15], 0x200
	s_mov_b64 s[16:17], 0x2000
	v_mov_b32_e32 v204, 1
	v_add_u32_e32 v205, s27, v125
	v_add_u32_e32 v206, s27, v126
	v_add_u32_e32 v207, s27, v127
	s_mov_b32 s27, 0
	s_waitcnt lgkmcnt(0)
	s_barrier
	s_branch .LBB0_699

; #define LAS __attribute__((address_space(3)))
; __device__ __forceinline__ float bflo(unsigned w) { return __uint_as_float(w << 16); }
; __device__ __forceinline__ float bfhi(unsigned w) { return __uint_as_float(w & 0xffff0000u); }
; __device__ __forceinline__ unsigned pk2(float lo, float hi) { return f2bf(lo) | (f2bf(hi) << 16); }
; template <bool FULL>
; __device__ __forceinline__ void gla_pass(const Params& P, LAS unsigned char* lds, f32x4 (&S)[8][2], int bh, int c0, int L, bool dry) {
;     ...
;         if (FULL) {
;             f32x4 gn[2];
; #pragma unroll
;             for (int vt = 0; vt < 2; ++vt) gn[vt] = *(const f32x4*)(P.gla_norm_g + 32 * w + 4 * g + 16 * vt);
; #pragma unroll
;             for (int tt = 0; tt < 4; ++tt) {
;                 const int t = 16 * tt + fr;
;                 const f32x4 r0 = *(const LAS f32x4*)(red + t * 8), r1 = *(const LAS f32x4*)(red + t * 8 + 4);
;                 const float rstd = 1.0f / sqrtf(((r0[0] + r0[1]) + (r0[2] + r0[3]) + (r1[0] + r1[1]) + (r1[2] + r1[3])) * (1.0f / 256.0f) + RMS_EPS);
; #pragma unroll
;                 for (int vt = 0; vt < 2; ++vt) {
;                     bf16_t* op = (bf16_t*)P.out + (row0 + t) * 2048 + 1024 + h * 256 + 32 * w + 16 * vt + 4 * g;
;                     const u32x2 z = zb[vt][tt]; const f32x4 ov = o[vt][tt] * rstd * gn[vt];
;                     u32x2 r; r.x = pk2(ov[0] * bflo(z.x), ov[1] * bfhi(z.x)); r.y = pk2(ov[2] * bflo(z.y), ov[3] * bfhi(z.y));
;                     if (!dry) *(u32x2*)op = r;
;                 }
;             }
.LBB0_698:
	v_mov_b32_e32 v140, v238
	v_mov_b32_e32 v141, v239
	v_mov_b32_e32 v142, v240
	v_mov_b32_e32 v143, v241
	v_mov_b32_e32 v136, v242
	v_mov_b32_e32 v137, v243
	v_mov_b32_e32 v138, v244
	v_mov_b32_e32 v139, v245
	ds_read_b128 v[208:211], v190
	ds_read_b128 v[212:215], v190 offset:16
	s_waitcnt vmcnt(7)
	v_lshlrev_b32_e32 v217, 16, v181
	v_lshlrev_b32_e32 v216, 16, v180
	v_and_b32_e32 v181, 0xffff0000, v181
	s_waitcnt lgkmcnt(1)
	v_mov_b32_e32 v220, v209
	v_mov_b32_e32 v221, v210
	v_mov_b32_e32 v209, v211
	s_waitcnt lgkmcnt(0)
	v_mov_b32_e32 v210, v214
	v_mov_b32_e32 v211, v212
	v_mov_b32_e32 v212, v215
	v_pk_add_f32 v[208:209], v[220:221], v[208:209]
	v_pk_add_f32 v[210:211], v[210:211], v[212:213]
	v_add_f32_e32 v208, v208, v209
	v_add_f32_e32 v208, v208, v211
	v_add_f32_e32 v208, v210, v208
	v_fmamk_f32 v208, v208, 0x3b800000, v202
	v_mul_f32_e32 v209, 0x4f800000, v208
	v_cmp_gt_f32_e32 vcc, s26, v208
	v_and_b32_e32 v180, 0xffff0000, v180
	s_waitcnt vmcnt(4)
	v_lshlrev_b32_e32 v219, 16, v179
	v_cndmask_b32_e32 v210, v208, v209, vcc
	v_sqrt_f32_e32 v211, v210
	v_lshlrev_b32_e32 v218, 16, v178
	v_and_b32_e32 v179, 0xffff0000, v179
	v_and_b32_e32 v178, 0xffff0000, v178
	v_add_u32_e32 v212, -1, v211
	v_add_u32_e32 v213, 1, v211
	v_fma_f32 v214, -v212, v211, v210
	v_fma_f32 v215, -v213, v211, v210
	v_cmp_ge_f32_e64 s[8:9], 0, v214
	v_add_u32_e32 v160, s27, v193
	v_lshlrev_b64 v[208:209], 12, v[160:161]
	v_cndmask_b32_e64 v211, v211, v212, s[8:9]
	v_cmp_lt_f32_e64 s[8:9], 0, v215
	v_lshl_add_u64 v[208:209], v[168:169], 0, v[208:209]
	s_add_i32 s27, s27, 64
	v_cndmask_b32_e64 v211, v211, v213, s[8:9]
	v_mul_f32_e32 v212, 0x37800000, v211
	v_cndmask_b32_e32 v211, v211, v212, vcc
	v_cmp_class_f32_e32 vcc, v210, v203
	s_add_i32 s0, s0, 1
	v_lshl_add_u64 v[170:171], v[170:171], 0, s[14:15]
	v_cndmask_b32_e32 v210, v211, v210, vcc
	v_div_scale_f32 v211, s[8:9], v210, v210, 1.0
	v_rcp_f32_e32 v212, v211
	v_div_scale_f32 v213, vcc, 1.0, v210, 1.0
	s_cmpk_eq_i32 s27, 0x400
	v_fma_f32 v214, -v211, v212, 1.0
	v_fmac_f32_e32 v212, v214, v212
	v_mul_f32_e32 v214, v213, v212
	v_fma_f32 v215, -v211, v214, v213
	v_fmac_f32_e32 v214, v215, v212
	v_fma_f32 v211, -v211, v214, v213
	v_div_fmas_f32 v211, v211, v212, v214
	v_div_fixup_f32 v210, v211, v210, 1.0
	v_pk_mul_f32 v[134:135], v[134:135], v[210:211] op_sel_hi:[1,0]
	v_pk_mul_f32 v[132:133], v[132:133], v[210:211] op_sel_hi:[1,0]
	v_pk_mul_f32 v[130:131], v[130:131], v[210:211] op_sel_hi:[1,0]
	v_pk_mul_f32 v[128:129], v[128:129], v[210:211] op_sel_hi:[1,0]
	v_lshl_add_u64 v[172:173], v[172:173], 0, s[16:17]
	s_waitcnt vmcnt(0)
	v_pk_mul_f32 v[132:133], v[140:141], v[132:133]
	v_pk_mul_f32 v[134:135], v[142:143], v[134:135]
	v_pk_mul_f32 v[128:129], v[136:137], v[128:129]
	v_pk_mul_f32 v[130:131], v[138:139], v[130:131]
	v_mov_b32_e32 v210, v132
	v_mov_b32_e32 v211, v134
	v_mov_b32_e32 v134, v133
	v_mov_b32_e32 v132, v128
	v_mov_b32_e32 v133, v130
	v_mov_b32_e32 v130, v129
	v_pk_mul_f32 v[128:129], v[210:211], v[216:217]
	v_pk_mul_f32 v[134:135], v[134:135], v[180:181]
	v_pk_mul_f32 v[178:179], v[130:131], v[178:179]
	v_and_b32_sdwa v130, v129, v204 dst_sel:DWORD dst_unused:UNUSED_PAD src0_sel:WORD_1 src1_sel:DWORD
	v_and_b32_sdwa v131, v128, v204 dst_sel:DWORD dst_unused:UNUSED_PAD src0_sel:WORD_1 src1_sel:DWORD
	v_and_b32_sdwa v180, v135, v204 dst_sel:DWORD dst_unused:UNUSED_PAD src0_sel:WORD_1 src1_sel:DWORD
	v_and_b32_sdwa v181, v134, v204 dst_sel:DWORD dst_unused:UNUSED_PAD src0_sel:WORD_1 src1_sel:DWORD
	v_add3_u32 v128, v128, v131, s1
	v_add3_u32 v129, v129, v130, s1
	v_add3_u32 v130, v135, v180, s1
	v_add3_u32 v131, v134, v181, s1
	v_and_b32_e32 v130, 0xffff0000, v130
	v_and_b32_e32 v131, 0xffff0000, v131
	v_pk_mul_f32 v[132:133], v[132:133], v[218:219]
	v_or_b32_sdwa v129, v130, v129 dst_sel:DWORD dst_unused:UNUSED_PAD src0_sel:DWORD src1_sel:WORD_1
	v_or_b32_sdwa v128, v131, v128 dst_sel:DWORD dst_unused:UNUSED_PAD src0_sel:DWORD src1_sel:WORD_1
	global_store_dwordx2 v[208:209], v[128:129], off offset:2048
	v_and_b32_sdwa v128, v133, v204 dst_sel:DWORD dst_unused:UNUSED_PAD src0_sel:WORD_1 src1_sel:DWORD
	v_and_b32_sdwa v129, v132, v204 dst_sel:DWORD dst_unused:UNUSED_PAD src0_sel:WORD_1 src1_sel:DWORD
	v_add3_u32 v210, v132, v129, s1
	v_add3_u32 v211, v133, v128, s1
	ds_read_b128 v[128:131], v205
	v_and_b32_sdwa v132, v179, v204 dst_sel:DWORD dst_unused:UNUSED_PAD src0_sel:WORD_1 src1_sel:DWORD
	v_add3_u32 v179, v179, v132, s1
	ds_read_b128 v[132:135], v205 offset:16
	v_and_b32_sdwa v212, v178, v204 dst_sel:DWORD dst_unused:UNUSED_PAD src0_sel:WORD_1 src1_sel:DWORD
	s_waitcnt lgkmcnt(1)
	v_mov_b32_e32 v180, v129
	v_mov_b32_e32 v181, v130
	v_mov_b32_e32 v129, v131
	v_pk_add_f32 v[128:129], v[180:181], v[128:129]
	s_waitcnt lgkmcnt(0)
; #define LAS __attribute__((address_space(3)))
; __device__ __forceinline__ float bflo(unsigned w) { return __uint_as_float(w << 16); }
; __device__ __forceinline__ float bfhi(unsigned w) { return __uint_as_float(w & 0xffff0000u); }
; __device__ __forceinline__ unsigned pk2(float lo, float hi) { return f2bf(lo) | (f2bf(hi) << 16); }
; template <bool FULL>
; __device__ __forceinline__ void gla_pass(const Params& P, LAS unsigned char* lds, f32x4 (&S)[8][2], int bh, int c0, int L, bool dry) {
;     ...
;             for (int tt = 0; tt < 4; ++tt) {
;                 const int t = 16 * tt + fr;
;                 const f32x4 r0 = *(const LAS f32x4*)(red + t * 8), r1 = *(const LAS f32x4*)(red + t * 8 + 4);
;                 const float rstd = 1.0f / sqrtf(((r0[0] + r0[1]) + (r0[2] + r0[3]) + (r1[0] + r1[1]) + (r1[2] + r1[3])) * (1.0f / 256.0f) + RMS_EPS);
; #pragma unroll
;                 for (int vt = 0; vt < 2; ++vt) {
;                     bf16_t* op = (bf16_t*)P.out + (row0 + t) * 2048 + 1024 + h * 256 + 32 * w + 16 * vt + 4 * g;
;                     const u32x2 z = zb[vt][tt]; const f32x4 ov = o[vt][tt] * rstd * gn[vt];
;                     u32x2 r; r.x = pk2(ov[0] * bflo(z.x), ov[1] * bfhi(z.x)); r.y = pk2(ov[2] * bflo(z.y), ov[3] * bfhi(z.y));
;                     if (!dry) *(u32x2*)op = r;
;                 }
	v_mov_b32_e32 v130, v134
	v_mov_b32_e32 v131, v132
	v_mov_b32_e32 v132, v135
	v_pk_add_f32 v[130:131], v[130:131], v[132:133]
	v_add_f32_e32 v128, v128, v129
	v_add_f32_e32 v128, v128, v131
	v_add_f32_e32 v128, v130, v128
	v_fmamk_f32 v128, v128, 0x3b800000, v202
	v_mul_f32_e32 v129, 0x4f800000, v128
	v_cmp_gt_f32_e32 vcc, s26, v128
	v_add3_u32 v130, v178, v212, s1
	v_and_b32_e32 v131, 0xffff0000, v179
	v_cndmask_b32_e32 v128, v128, v129, vcc
	v_sqrt_f32_e32 v129, v128
	v_and_b32_e32 v130, 0xffff0000, v130
	v_add_u32_e32 v132, -1, v129
	v_fma_f32 v133, -v132, v129, v128
	v_cmp_ge_f32_e64 s[8:9], 0, v133
	v_add_u32_e32 v133, 1, v129
	s_nop 0
	v_cndmask_b32_e64 v132, v129, v132, s[8:9]
	v_fma_f32 v129, -v133, v129, v128
	v_cmp_lt_f32_e64 s[8:9], 0, v129
	s_nop 1
	v_cndmask_b32_e64 v129, v132, v133, s[8:9]
	v_mul_f32_e32 v132, 0x37800000, v129
	v_cndmask_b32_e32 v129, v129, v132, vcc
	v_cmp_class_f32_e32 vcc, v128, v203
	s_nop 1
	v_cndmask_b32_e32 v132, v129, v128, vcc
	v_div_scale_f32 v133, s[8:9], v132, v132, 1.0
	v_rcp_f32_e32 v134, v133
	v_or_b32_sdwa v129, v131, v211 dst_sel:DWORD dst_unused:UNUSED_PAD src0_sel:DWORD src1_sel:WORD_1
	v_or_b32_sdwa v128, v130, v210 dst_sel:DWORD dst_unused:UNUSED_PAD src0_sel:DWORD src1_sel:WORD_1
	global_store_dwordx2 v[208:209], v[128:129], off offset:2080
	v_fma_f32 v128, -v133, v134, 1.0
	v_fmac_f32_e32 v134, v128, v134
	v_div_scale_f32 v128, vcc, 1.0, v132, 1.0
	v_mul_f32_e32 v129, v128, v134
	v_fma_f32 v130, -v133, v129, v128
	v_fmac_f32_e32 v129, v130, v134
	v_fma_f32 v128, -v133, v129, v128
	v_div_fmas_f32 v128, v128, v134, v129
	v_div_fixup_f32 v128, v128, v132, 1.0
	v_pk_mul_f32 v[126:127], v[126:127], v[128:129] op_sel_hi:[1,0]
	v_pk_mul_f32 v[124:125], v[124:125], v[128:129] op_sel_hi:[1,0]
	v_pk_mul_f32 v[126:127], v[142:143], v[126:127]
	v_pk_mul_f32 v[124:125], v[140:141], v[124:125]
	v_lshlrev_b32_e32 v133, 16, v177
	v_lshlrev_b32_e32 v132, 16, v176
	v_mov_b32_e32 v134, v124
	v_mov_b32_e32 v135, v126
	v_pk_mul_f32 v[132:133], v[134:135], v[132:133]
	v_and_b32_e32 v135, 0xffff0000, v177
	v_and_b32_e32 v134, 0xffff0000, v176
	v_mov_b32_e32 v126, v125
	v_pk_mul_f32 v[124:125], v[126:127], v[134:135]
	v_and_b32_sdwa v127, v132, v204 dst_sel:DWORD dst_unused:UNUSED_PAD src0_sel:WORD_1 src1_sel:DWORD
	v_add3_u32 v127, v132, v127, s1
	v_and_b32_sdwa v129, v125, v204 dst_sel:DWORD dst_unused:UNUSED_PAD src0_sel:WORD_1 src1_sel:DWORD
	v_and_b32_sdwa v132, v124, v204 dst_sel:DWORD dst_unused:UNUSED_PAD src0_sel:WORD_1 src1_sel:DWORD
	v_add_u32_e32 v130, 16, v160
	v_mov_b32_e32 v131, v161
	v_and_b32_sdwa v126, v133, v204 dst_sel:DWORD dst_unused:UNUSED_PAD src0_sel:WORD_1 src1_sel:DWORD
	v_add3_u32 v125, v125, v129, s1
	v_add3_u32 v124, v124, v132, s1
	v_lshlrev_b64 v[130:131], 12, v[130:131]
	v_add3_u32 v126, v133, v126, s1
	v_and_b32_e32 v125, 0xffff0000, v125
	v_and_b32_e32 v124, 0xffff0000, v124
	v_pk_mul_f32 v[122:123], v[122:123], v[128:129] op_sel_hi:[1,0]
	v_pk_mul_f32 v[120:121], v[120:121], v[128:129] op_sel_hi:[1,0]
	v_or_b32_sdwa v125, v125, v126 dst_sel:DWORD dst_unused:UNUSED_PAD src0_sel:DWORD src1_sel:WORD_1
	v_or_b32_sdwa v124, v124, v127 dst_sel:DWORD dst_unused:UNUSED_PAD src0_sel:DWORD src1_sel:WORD_1
	v_lshl_add_u64 v[130:131], v[168:169], 0, v[130:131]
	v_pk_mul_f32 v[120:121], v[136:137], v[120:121]
	v_pk_mul_f32 v[122:123], v[138:139], v[122:123]
	global_store_dwordx2 v[130:131], v[124:125], off offset:2048
	v_lshlrev_b32_e32 v125, 16, v175
	v_lshlrev_b32_e32 v124, 16, v174
	v_mov_b32_e32 v126, v120
	v_mov_b32_e32 v127, v122
	v_pk_mul_f32 v[124:125], v[126:127], v[124:125]
	v_and_b32_e32 v127, 0xffff0000, v175
	v_and_b32_e32 v126, 0xffff0000, v174
	v_mov_b32_e32 v122, v121
	v_pk_mul_f32 v[128:129], v[122:123], v[126:127]
	v_and_b32_sdwa v120, v125, v204 dst_sel:DWORD dst_unused:UNUSED_PAD src0_sel:WORD_1 src1_sel:DWORD
	v_and_b32_sdwa v121, v124, v204 dst_sel:DWORD dst_unused:UNUSED_PAD src0_sel:WORD_1 src1_sel:DWORD
	v_add3_u32 v134, v124, v121, s1
	v_add3_u32 v135, v125, v120, s1
	ds_read_b128 v[120:123], v206
	v_and_b32_sdwa v124, v129, v204 dst_sel:DWORD dst_unused:UNUSED_PAD src0_sel:WORD_1 src1_sel:DWORD
	v_add3_u32 v129, v129, v124, s1
	ds_read_b128 v[124:127], v206 offset:16
	v_and_b32_sdwa v174, v128, v204 dst_sel:DWORD dst_unused:UNUSED_PAD src0_sel:WORD_1 src1_sel:DWORD
	s_waitcnt lgkmcnt(1)
	v_mov_b32_e32 v132, v121
	v_mov_b32_e32 v133, v122
	v_mov_b32_e32 v121, v123
	v_pk_add_f32 v[120:121], v[132:133], v[120:121]
	s_waitcnt lgkmcnt(0)
; #define LAS __attribute__((address_space(3)))
; __device__ __forceinline__ float bflo(unsigned w) { return __uint_as_float(w << 16); }
; __device__ __forceinline__ float bfhi(unsigned w) { return __uint_as_float(w & 0xffff0000u); }
; __device__ __forceinline__ unsigned pk2(float lo, float hi) { return f2bf(lo) | (f2bf(hi) << 16); }
; template <bool FULL>
; __device__ __forceinline__ void gla_pass(const Params& P, LAS unsigned char* lds, f32x4 (&S)[8][2], int bh, int c0, int L, bool dry) {
;     ...
;             for (int tt = 0; tt < 4; ++tt) {
;                 const int t = 16 * tt + fr;
;                 const f32x4 r0 = *(const LAS f32x4*)(red + t * 8), r1 = *(const LAS f32x4*)(red + t * 8 + 4);
;                 const float rstd = 1.0f / sqrtf(((r0[0] + r0[1]) + (r0[2] + r0[3]) + (r1[0] + r1[1]) + (r1[2] + r1[3])) * (1.0f / 256.0f) + RMS_EPS);
; #pragma unroll
;                 for (int vt = 0; vt < 2; ++vt) {
;                     bf16_t* op = (bf16_t*)P.out + (row0 + t) * 2048 + 1024 + h * 256 + 32 * w + 16 * vt + 4 * g;
;                     const u32x2 z = zb[vt][tt]; const f32x4 ov = o[vt][tt] * rstd * gn[vt];
;                     u32x2 r; r.x = pk2(ov[0] * bflo(z.x), ov[1] * bfhi(z.x)); r.y = pk2(ov[2] * bflo(z.y), ov[3] * bfhi(z.y));
;                     if (!dry) *(u32x2*)op = r;
;                 }
	v_mov_b32_e32 v122, v126
	v_mov_b32_e32 v123, v124
	v_mov_b32_e32 v124, v127
	v_pk_add_f32 v[122:123], v[122:123], v[124:125]
	v_add_f32_e32 v120, v120, v121
	v_add_f32_e32 v120, v120, v123
	v_add_f32_e32 v120, v122, v120
	v_fmamk_f32 v120, v120, 0x3b800000, v202
	v_mul_f32_e32 v121, 0x4f800000, v120
	v_cmp_gt_f32_e32 vcc, s26, v120
	v_add3_u32 v122, v128, v174, s1
	v_and_b32_e32 v123, 0xffff0000, v129
	v_cndmask_b32_e32 v120, v120, v121, vcc
	v_sqrt_f32_e32 v121, v120
	v_and_b32_e32 v122, 0xffff0000, v122
	v_add_u32_e32 v124, -1, v121
	v_fma_f32 v125, -v124, v121, v120
	v_cmp_ge_f32_e64 s[8:9], 0, v125
	v_add_u32_e32 v125, 1, v121
	s_nop 0
	v_cndmask_b32_e64 v124, v121, v124, s[8:9]
	v_fma_f32 v121, -v125, v121, v120
	v_cmp_lt_f32_e64 s[8:9], 0, v121
	s_nop 1
	v_cndmask_b32_e64 v121, v124, v125, s[8:9]
	v_mul_f32_e32 v124, 0x37800000, v121
	v_cndmask_b32_e32 v121, v121, v124, vcc
	v_cmp_class_f32_e32 vcc, v120, v203
	s_nop 1
	v_cndmask_b32_e32 v124, v121, v120, vcc
	v_div_scale_f32 v125, s[8:9], v124, v124, 1.0
	v_rcp_f32_e32 v126, v125
	v_or_b32_sdwa v121, v123, v135 dst_sel:DWORD dst_unused:UNUSED_PAD src0_sel:DWORD src1_sel:WORD_1
	v_or_b32_sdwa v120, v122, v134 dst_sel:DWORD dst_unused:UNUSED_PAD src0_sel:DWORD src1_sel:WORD_1
	global_store_dwordx2 v[130:131], v[120:121], off offset:2080
	v_fma_f32 v120, -v125, v126, 1.0
	v_fmac_f32_e32 v126, v120, v126
	v_div_scale_f32 v120, vcc, 1.0, v124, 1.0
	v_mul_f32_e32 v121, v120, v126
	v_fma_f32 v122, -v125, v121, v120
	v_fmac_f32_e32 v121, v122, v126
	v_fma_f32 v120, -v125, v121, v120
	v_div_fmas_f32 v120, v120, v126, v121
	v_div_fixup_f32 v120, v120, v124, 1.0
	v_pk_mul_f32 v[110:111], v[110:111], v[120:121] op_sel_hi:[1,0]
	v_pk_mul_f32 v[108:109], v[108:109], v[120:121] op_sel_hi:[1,0]
	v_pk_mul_f32 v[110:111], v[142:143], v[110:111]
	v_pk_mul_f32 v[108:109], v[140:141], v[108:109]
	v_lshlrev_b32_e32 v125, 16, v151
	v_lshlrev_b32_e32 v124, 16, v150
	v_mov_b32_e32 v126, v108
	v_mov_b32_e32 v127, v110
	v_pk_mul_f32 v[124:125], v[126:127], v[124:125]
	v_and_b32_e32 v127, 0xffff0000, v151
	v_and_b32_e32 v126, 0xffff0000, v150
	v_mov_b32_e32 v110, v109
	v_pk_mul_f32 v[108:109], v[110:111], v[126:127]
	v_and_b32_sdwa v111, v124, v204 dst_sel:DWORD dst_unused:UNUSED_PAD src0_sel:WORD_1 src1_sel:DWORD
	v_add3_u32 v111, v124, v111, s1
	v_and_b32_sdwa v121, v109, v204 dst_sel:DWORD dst_unused:UNUSED_PAD src0_sel:WORD_1 src1_sel:DWORD
	v_and_b32_sdwa v124, v108, v204 dst_sel:DWORD dst_unused:UNUSED_PAD src0_sel:WORD_1 src1_sel:DWORD
	v_add_u32_e32 v122, 32, v160
	v_mov_b32_e32 v123, v161
	v_and_b32_sdwa v110, v125, v204 dst_sel:DWORD dst_unused:UNUSED_PAD src0_sel:WORD_1 src1_sel:DWORD
	v_add3_u32 v109, v109, v121, s1
	v_add3_u32 v108, v108, v124, s1
	v_lshlrev_b64 v[122:123], 12, v[122:123]
	v_add3_u32 v110, v125, v110, s1
	v_and_b32_e32 v109, 0xffff0000, v109
	v_and_b32_e32 v108, 0xffff0000, v108
	v_pk_mul_f32 v[106:107], v[106:107], v[120:121] op_sel_hi:[1,0]
	v_pk_mul_f32 v[104:105], v[104:105], v[120:121] op_sel_hi:[1,0]
	v_or_b32_sdwa v109, v109, v110 dst_sel:DWORD dst_unused:UNUSED_PAD src0_sel:DWORD src1_sel:WORD_1
	v_or_b32_sdwa v108, v108, v111 dst_sel:DWORD dst_unused:UNUSED_PAD src0_sel:DWORD src1_sel:WORD_1
	v_lshl_add_u64 v[122:123], v[168:169], 0, v[122:123]
	v_pk_mul_f32 v[104:105], v[136:137], v[104:105]
	v_pk_mul_f32 v[106:107], v[138:139], v[106:107]
	global_store_dwordx2 v[122:123], v[108:109], off offset:2048
	v_lshlrev_b32_e32 v109, 16, v149
	v_lshlrev_b32_e32 v108, 16, v148
	v_mov_b32_e32 v110, v104
	v_mov_b32_e32 v111, v106
	v_pk_mul_f32 v[108:109], v[110:111], v[108:109]
	v_and_b32_e32 v111, 0xffff0000, v149
	v_and_b32_e32 v110, 0xffff0000, v148
	v_mov_b32_e32 v106, v105
	v_pk_mul_f32 v[120:121], v[106:107], v[110:111]
	v_and_b32_sdwa v104, v109, v204 dst_sel:DWORD dst_unused:UNUSED_PAD src0_sel:WORD_1 src1_sel:DWORD
	v_and_b32_sdwa v105, v108, v204 dst_sel:DWORD dst_unused:UNUSED_PAD src0_sel:WORD_1 src1_sel:DWORD
	v_add3_u32 v126, v108, v105, s1
	v_add3_u32 v127, v109, v104, s1
	ds_read_b128 v[104:107], v207
	v_and_b32_sdwa v108, v121, v204 dst_sel:DWORD dst_unused:UNUSED_PAD src0_sel:WORD_1 src1_sel:DWORD
	v_add3_u32 v121, v121, v108, s1
	ds_read_b128 v[108:111], v207 offset:16
	v_and_b32_sdwa v128, v120, v204 dst_sel:DWORD dst_unused:UNUSED_PAD src0_sel:WORD_1 src1_sel:DWORD
	s_waitcnt lgkmcnt(1)
	v_mov_b32_e32 v124, v105
	v_mov_b32_e32 v125, v106
	v_mov_b32_e32 v105, v107
	v_pk_add_f32 v[104:105], v[124:125], v[104:105]
	s_waitcnt lgkmcnt(0)
; #define LAS __attribute__((address_space(3)))
; __device__ __forceinline__ float bflo(unsigned w) { return __uint_as_float(w << 16); }
; __device__ __forceinline__ float bfhi(unsigned w) { return __uint_as_float(w & 0xffff0000u); }
; __device__ __forceinline__ unsigned pk2(float lo, float hi) { return f2bf(lo) | (f2bf(hi) << 16); }
; template <bool FULL>
; __device__ __forceinline__ void gla_pass(const Params& P, LAS unsigned char* lds, f32x4 (&S)[8][2], int bh, int c0, int L, bool dry) {
;     ...
;             for (int tt = 0; tt < 4; ++tt) {
;                 const int t = 16 * tt + fr;
;                 const f32x4 r0 = *(const LAS f32x4*)(red + t * 8), r1 = *(const LAS f32x4*)(red + t * 8 + 4);
;                 const float rstd = 1.0f / sqrtf(((r0[0] + r0[1]) + (r0[2] + r0[3]) + (r1[0] + r1[1]) + (r1[2] + r1[3])) * (1.0f / 256.0f) + RMS_EPS);
; #pragma unroll
;                 for (int vt = 0; vt < 2; ++vt) {
;                     bf16_t* op = (bf16_t*)P.out + (row0 + t) * 2048 + 1024 + h * 256 + 32 * w + 16 * vt + 4 * g;
;                     const u32x2 z = zb[vt][tt]; const f32x4 ov = o[vt][tt] * rstd * gn[vt];
;                     u32x2 r; r.x = pk2(ov[0] * bflo(z.x), ov[1] * bfhi(z.x)); r.y = pk2(ov[2] * bflo(z.y), ov[3] * bfhi(z.y));
;                     if (!dry) *(u32x2*)op = r;
;                 }
;             }
;         }
;         __syncthreads();
	v_mov_b32_e32 v106, v110
	v_mov_b32_e32 v107, v108
	v_mov_b32_e32 v108, v111
	v_pk_add_f32 v[106:107], v[106:107], v[108:109]
	v_add_f32_e32 v104, v104, v105
	v_add_f32_e32 v104, v104, v107
	v_add_f32_e32 v104, v106, v104
	v_fmamk_f32 v104, v104, 0x3b800000, v202
	v_mul_f32_e32 v105, 0x4f800000, v104
	v_cmp_gt_f32_e32 vcc, s26, v104
	v_add3_u32 v106, v120, v128, s1
	v_and_b32_e32 v107, 0xffff0000, v121
	v_cndmask_b32_e32 v104, v104, v105, vcc
	v_sqrt_f32_e32 v105, v104
	v_and_b32_e32 v106, 0xffff0000, v106
	v_add_u32_e32 v160, 48, v160
	v_add_u32_e32 v108, -1, v105
	v_fma_f32 v109, -v108, v105, v104
	v_cmp_ge_f32_e64 s[8:9], 0, v109
	v_add_u32_e32 v109, 1, v105
	s_nop 0
	v_cndmask_b32_e64 v108, v105, v108, s[8:9]
	v_fma_f32 v105, -v109, v105, v104
	v_cmp_lt_f32_e64 s[8:9], 0, v105
	s_nop 1
	v_cndmask_b32_e64 v105, v108, v109, s[8:9]
	v_mul_f32_e32 v108, 0x37800000, v105
	v_cndmask_b32_e32 v105, v105, v108, vcc
	v_cmp_class_f32_e32 vcc, v104, v203
	s_nop 1
	v_cndmask_b32_e32 v108, v105, v104, vcc
	v_div_scale_f32 v109, s[8:9], v108, v108, 1.0
	v_rcp_f32_e32 v110, v109
	v_or_b32_sdwa v105, v107, v127 dst_sel:DWORD dst_unused:UNUSED_PAD src0_sel:DWORD src1_sel:WORD_1
	v_or_b32_sdwa v104, v106, v126 dst_sel:DWORD dst_unused:UNUSED_PAD src0_sel:DWORD src1_sel:WORD_1
	global_store_dwordx2 v[122:123], v[104:105], off offset:2080
	v_fma_f32 v104, -v109, v110, 1.0
	v_fmac_f32_e32 v110, v104, v110
	v_div_scale_f32 v104, vcc, 1.0, v108, 1.0
	v_mul_f32_e32 v105, v104, v110
	v_fma_f32 v106, -v109, v105, v104
	v_fmac_f32_e32 v105, v106, v110
	v_fma_f32 v104, -v109, v105, v104
	v_div_fmas_f32 v104, v104, v110, v105
	v_div_fixup_f32 v104, v104, v108, 1.0
	v_pk_mul_f32 v[108:109], v[118:119], v[104:105] op_sel_hi:[1,0]
	v_pk_mul_f32 v[110:111], v[116:117], v[104:105] op_sel_hi:[1,0]
	v_pk_mul_f32 v[108:109], v[142:143], v[108:109]
	v_pk_mul_f32 v[110:111], v[140:141], v[110:111]
	v_lshlrev_b32_e32 v117, 16, v147
	v_lshlrev_b32_e32 v116, 16, v146
	v_mov_b32_e32 v118, v110
	v_mov_b32_e32 v119, v108
	v_pk_mul_f32 v[116:117], v[118:119], v[116:117]
	v_and_b32_e32 v119, 0xffff0000, v147
	v_and_b32_e32 v118, 0xffff0000, v146
	v_mov_b32_e32 v108, v111
	v_pk_mul_f32 v[108:109], v[108:109], v[118:119]
	v_and_b32_sdwa v110, v116, v204 dst_sel:DWORD dst_unused:UNUSED_PAD src0_sel:WORD_1 src1_sel:DWORD
	v_add3_u32 v110, v116, v110, s1
	v_and_b32_sdwa v111, v109, v204 dst_sel:DWORD dst_unused:UNUSED_PAD src0_sel:WORD_1 src1_sel:DWORD
	v_and_b32_sdwa v116, v108, v204 dst_sel:DWORD dst_unused:UNUSED_PAD src0_sel:WORD_1 src1_sel:DWORD
	v_and_b32_sdwa v105, v117, v204 dst_sel:DWORD dst_unused:UNUSED_PAD src0_sel:WORD_1 src1_sel:DWORD
	v_add3_u32 v109, v109, v111, s1
	v_add3_u32 v108, v108, v116, s1
	v_lshlrev_b64 v[106:107], 12, v[160:161]
	v_add3_u32 v105, v117, v105, s1
	v_and_b32_e32 v109, 0xffff0000, v109
	v_and_b32_e32 v108, 0xffff0000, v108
	v_or_b32_sdwa v109, v109, v105 dst_sel:DWORD dst_unused:UNUSED_PAD src0_sel:DWORD src1_sel:WORD_1
	v_or_b32_sdwa v108, v108, v110 dst_sel:DWORD dst_unused:UNUSED_PAD src0_sel:DWORD src1_sel:WORD_1
	v_lshl_add_u64 v[106:107], v[168:169], 0, v[106:107]
	global_store_dwordx2 v[106:107], v[108:109], off offset:2048
	v_pk_mul_f32 v[108:109], v[114:115], v[104:105] op_sel_hi:[1,0]
	v_pk_mul_f32 v[104:105], v[112:113], v[104:105] op_sel_hi:[1,0]
	v_pk_mul_f32 v[108:109], v[138:139], v[108:109]
	v_pk_mul_f32 v[104:105], v[136:137], v[104:105]
	v_lshlrev_b32_e32 v111, 16, v145
	v_lshlrev_b32_e32 v110, 16, v144
	v_mov_b32_e32 v112, v104
	v_mov_b32_e32 v113, v108
	v_pk_mul_f32 v[110:111], v[112:113], v[110:111]
	v_and_b32_e32 v113, 0xffff0000, v145
	v_and_b32_e32 v112, 0xffff0000, v144
	v_mov_b32_e32 v108, v105
	v_pk_mul_f32 v[104:105], v[108:109], v[112:113]
	v_and_b32_sdwa v108, v111, v204 dst_sel:DWORD dst_unused:UNUSED_PAD src0_sel:WORD_1 src1_sel:DWORD
	v_and_b32_sdwa v109, v110, v204 dst_sel:DWORD dst_unused:UNUSED_PAD src0_sel:WORD_1 src1_sel:DWORD
	v_add3_u32 v109, v110, v109, s1
	v_add3_u32 v108, v111, v108, s1
	v_and_b32_sdwa v110, v105, v204 dst_sel:DWORD dst_unused:UNUSED_PAD src0_sel:WORD_1 src1_sel:DWORD
	v_and_b32_sdwa v111, v104, v204 dst_sel:DWORD dst_unused:UNUSED_PAD src0_sel:WORD_1 src1_sel:DWORD
	v_add3_u32 v105, v105, v110, s1
	v_add3_u32 v104, v104, v111, s1
	v_and_b32_e32 v105, 0xffff0000, v105
	v_and_b32_e32 v104, 0xffff0000, v104
	v_or_b32_sdwa v105, v105, v108 dst_sel:DWORD dst_unused:UNUSED_PAD src0_sel:DWORD src1_sel:WORD_1
	v_or_b32_sdwa v104, v104, v109 dst_sel:DWORD dst_unused:UNUSED_PAD src0_sel:DWORD src1_sel:WORD_1
	global_store_dwordx2 v[106:107], v[104:105], off offset:2080
	s_barrier
	s_cbranch_scc1 .LBB0_714

; #define LAS __attribute__((address_space(3)))
; template <bool FULL>
; __device__ __forceinline__ void gla_pass(const Params& P, LAS unsigned char* lds, f32x4 (&S)[8][2], int bh, int c0, int L, bool dry) {
;     ...
;             for (int k2 = 0; k2 < 2; ++k2) vf[vt][k2] = trfrag(Lv, V_P, 32 * k2, (32 * w + 16 * vt) * 2, g, fr);
;         f32x4 o[2][4];
;         if (FULL) {
; #pragma unroll
;             for (int vt = 0; vt < 2; ++vt)
; #pragma unroll
;                 for (int tt = 0; tt < 4; ++tt) o[vt][tt] = (f32x4){0.f, 0.f, 0.f, 0.f};
; #pragma unroll
;             for (int k4 = 0; k4 < 4; ++k4) {
;                 const bf16x8 a0 = rowfrag(Lst, ST_P, 32 * w, 64 * k4, g, fr), a1 = rowfrag(Lst, ST_P, 32 * w + 16, 64 * k4, g, fr);
; #pragma unroll
;                 for (int tt = 0; tt < 4; ++tt) { const bf16x8 bq = rowfrag(Lqd, QD_P, 16 * tt, 64 * k4, g, fr);
;                     o[0][tt] = __builtin_amdgcn_mfma_f32_16x16x32_bf16(a0, bq, o[0][tt], 0, 0, 0); o[1][tt] = __builtin_amdgcn_mfma_f32_16x16x32_bf16(a1, bq, o[1][tt], 0, 0, 0); }
;             }
; #pragma unroll
;             for (int k2 = 0; k2 < 2; ++k2)
; #pragma unroll
;                 for (int tt = 0; tt < 4; ++tt) { const bf16x8 bp = rowfrag(Lp, P_P, 16 * tt, 64 * k2, g, fr);
;                     o[0][tt] = __builtin_amdgcn_mfma_f32_16x16x32_bf16(vf[0][k2], bp, o[0][tt], 0, 0, 0); o[1][tt] = __builtin_amdgcn_mfma_f32_16x16x32_bf16(vf[1][k2], bp, o[1][tt], 0, 0, 0); }
;         }
; #pragma unroll
;         for (int kt = 0; kt < 8; ++kt) { const f32x4 dv = *(const LAS f32x4*)(Ldec + 16 * kt + 4 * g); S[kt][0] = S[kt][0] * dv; S[kt][1] = S[kt][1] * dv; }
.LBB0_703:
	ds_read_b128 v[104:107], v197
	ds_read_b128 v[108:111], v198 offset:18432
	ds_read_b128 v[112:115], v197 offset:64
	ds_read_b128 v[116:119], v198 offset:18496
	ds_read_b128 v[124:127], v197 offset:4352
	ds_read_b128 v[128:131], v197 offset:4416
	ds_read_b128 v[132:135], v198 offset:22784
	ds_read_b128 v[136:139], v198 offset:22848
	ds_read_b128 v[144:147], v198 offset:27136
	ds_read_b128 v[148:151], v198 offset:27200
	ds_read_b128 v[178:181], v198 offset:31488
	ds_read_b128 v[208:211], v198 offset:31552
	s_waitcnt lgkmcnt(10)
	v_mfma_f32_16x16x32_bf16 v[120:123], v[104:107], v[108:111], 0
	v_add_u32_e32 v160, 0x25000, v187
	s_waitcnt lgkmcnt(7)
	v_mfma_f32_16x16x32_bf16 v[108:111], v[124:127], v[108:111], 0
	s_waitcnt lgkmcnt(5)
	v_mfma_f32_16x16x32_bf16 v[140:143], v[104:107], v[132:135], 0
	v_mfma_f32_16x16x32_bf16 v[132:135], v[124:127], v[132:135], 0
	s_waitcnt lgkmcnt(3)
	v_mfma_f32_16x16x32_bf16 v[174:177], v[104:107], v[144:147], 0
	s_waitcnt lgkmcnt(1)
	v_mfma_f32_16x16x32_bf16 v[104:107], v[104:107], v[178:181], 0
	v_mfma_f32_16x16x32_bf16 v[120:123], v[112:115], v[116:119], v[120:123]
	v_mfma_f32_16x16x32_bf16 v[108:111], v[128:131], v[116:119], v[108:111]
	v_mfma_f32_16x16x32_bf16 v[116:119], v[112:115], v[136:139], v[140:143]
	v_mfma_f32_16x16x32_bf16 v[132:135], v[128:131], v[136:139], v[132:135]
	v_mfma_f32_16x16x32_bf16 v[136:139], v[112:115], v[148:151], v[174:177]
	s_waitcnt lgkmcnt(0)
	v_mfma_f32_16x16x32_bf16 v[104:107], v[112:115], v[208:211], v[104:107]
	ds_read_b128 v[112:115], v197 offset:128
	v_mfma_f32_16x16x32_bf16 v[144:147], v[124:127], v[144:147], 0
	v_mfma_f32_16x16x32_bf16 v[124:127], v[124:127], v[178:181], 0
	v_mfma_f32_16x16x32_bf16 v[140:143], v[128:131], v[148:151], v[144:147]
	v_mfma_f32_16x16x32_bf16 v[124:127], v[128:131], v[208:211], v[124:127]
	ds_read_b128 v[128:131], v198 offset:18560
	s_nop 3
	ds_read_b128 v[144:147], v197 offset:192
	ds_read_b128 v[148:151], v198 offset:18624
	ds_read_b128 v[174:177], v197 offset:4480
	ds_read_b128 v[178:181], v197 offset:4544
	s_waitcnt lgkmcnt(4)
	v_mfma_f32_16x16x32_bf16 v[120:123], v[112:115], v[128:131], v[120:123]
	s_waitcnt lgkmcnt(1)
	v_mfma_f32_16x16x32_bf16 v[108:111], v[174:177], v[128:131], v[108:111]
	ds_read_b128 v[128:131], v198 offset:22912
	ds_read_b128 v[208:211], v198 offset:22976
	s_waitcnt lgkmcnt(1)
	v_mfma_f32_16x16x32_bf16 v[116:119], v[112:115], v[128:131], v[116:119]
	v_mfma_f32_16x16x32_bf16 v[128:131], v[174:177], v[128:131], v[132:135]
	s_nop 2
	ds_read_b128 v[132:135], v198 offset:27264
	ds_read_b128 v[212:215], v198 offset:27328
	s_waitcnt lgkmcnt(1)
	v_mfma_f32_16x16x32_bf16 v[136:139], v[112:115], v[132:135], v[136:139]
	v_mfma_f32_16x16x32_bf16 v[132:135], v[174:177], v[132:135], v[140:143]
	s_nop 2
	ds_read_b128 v[140:143], v198 offset:31616
	ds_read_b128 v[216:219], v198 offset:31680
	s_waitcnt lgkmcnt(1)
	v_mfma_f32_16x16x32_bf16 v[104:107], v[112:115], v[140:143], v[104:107]
	v_mfma_f32_16x16x32_bf16 v[112:115], v[174:177], v[140:143], v[124:127]
	v_mfma_f32_16x16x32_bf16 v[120:123], v[144:147], v[148:151], v[120:123]
	v_mfma_f32_16x16x32_bf16 v[108:111], v[178:181], v[148:151], v[108:111]
	v_mfma_f32_16x16x32_bf16 v[116:119], v[144:147], v[208:211], v[116:119]
	v_mfma_f32_16x16x32_bf16 v[124:127], v[178:181], v[208:211], v[128:131]
	v_mfma_f32_16x16x32_bf16 v[128:131], v[144:147], v[212:215], v[136:139]
	s_waitcnt lgkmcnt(0)
	v_mfma_f32_16x16x32_bf16 v[104:107], v[144:147], v[216:219], v[104:107]
	ds_read_b64_tr_b16 v[150:151], v196 offset:38016
	ds_read_b64_tr_b16 v[148:149], v196 offset:35840
	ds_read_b64_tr_b16 v[146:147], v196 offset:38048
	ds_read_b64_tr_b16 v[144:145], v196 offset:35872
	ds_read_b128 v[136:139], v199
	ds_read_b128 v[174:177], v199 offset:64
	v_mfma_f32_16x16x32_bf16 v[132:135], v[178:181], v[212:215], v[132:135]
	v_mfma_f32_16x16x32_bf16 v[112:115], v[178:181], v[216:219], v[112:115]
	s_waitcnt lgkmcnt(1)
	v_mfma_f32_16x16x32_bf16 v[120:123], v[148:151], v[136:139], v[120:123]
	v_mfma_f32_16x16x32_bf16 v[108:111], v[144:147], v[136:139], v[108:111]
	ds_read_b128 v[136:139], v199 offset:2304
	ds_read_b128 v[178:181], v199 offset:2368
	s_waitcnt lgkmcnt(1)
	v_mfma_f32_16x16x32_bf16 v[208:211], v[144:147], v[136:139], v[124:127]
	s_nop 2
	ds_read_b128 v[124:127], v199 offset:4608
	ds_read_b128 v[212:215], v199 offset:4672
	v_mfma_f32_16x16x32_bf16 v[116:119], v[148:151], v[136:139], v[116:119]
	s_waitcnt lgkmcnt(1)
	v_mfma_f32_16x16x32_bf16 v[216:219], v[148:151], v[124:127], v[128:131]
	v_mfma_f32_16x16x32_bf16 v[220:223], v[144:147], v[124:127], v[132:135]
	ds_read_b128 v[124:127], v199 offset:6912
	ds_read_b128 v[224:227], v199 offset:6976
	ds_read_b64_tr_b16 v[140:141], v196 offset:53248
	ds_read_b64_tr_b16 v[142:143], v196 offset:55424
	ds_read_b64_tr_b16 v[138:139], v196 offset:55456
	ds_read_b64_tr_b16 v[136:137], v196 offset:53280
	s_waitcnt lgkmcnt(5)
	v_mfma_f32_16x16x32_bf16 v[228:231], v[148:151], v[124:127], v[104:107]
	v_mfma_f32_16x16x32_bf16 v[112:115], v[144:147], v[124:127], v[112:115]
	s_waitcnt lgkmcnt(2)
	v_mfma_f32_16x16x32_bf16 v[132:135], v[140:143], v[174:177], v[120:123]
	s_waitcnt lgkmcnt(0)
	v_mfma_f32_16x16x32_bf16 v[128:131], v[136:139], v[174:177], v[108:111]
	ds_read_b128 v[174:177], v160
	v_mfma_f32_16x16x32_bf16 v[124:127], v[140:143], v[178:181], v[116:119]
	v_mfma_f32_16x16x32_bf16 v[120:123], v[136:139], v[178:181], v[208:211]
	ds_read_b128 v[178:181], v160 offset:64
	s_waitcnt lgkmcnt(1)
; #define LAS __attribute__((address_space(3)))
; template <bool FULL>
; __device__ __forceinline__ void gla_pass(const Params& P, LAS unsigned char* lds, f32x4 (&S)[8][2], int bh, int c0, int L, bool dry) {
;     ...
;         for (int kt = 0; kt < 8; ++kt) { const f32x4 dv = *(const LAS f32x4*)(Ldec + 16 * kt + 4 * g); S[kt][0] = S[kt][0] * dv; S[kt][1] = S[kt][1] * dv; }
; #pragma unroll
;         for (int k2 = 0; k2 < 2; ++k2)
; #pragma unroll
;             for (int kt = 0; kt < 8; ++kt) { const bf16x8 ak = trfrag(Lks, KS_P, 32 * k2, 32 * kt, g, fr);
;                 S[kt][0] = __builtin_amdgcn_mfma_f32_16x16x32_bf16(ak, vf[0][k2], S[kt][0], 0, 0, 0); S[kt][1] = __builtin_amdgcn_mfma_f32_16x16x32_bf16(ak, vf[1][k2], S[kt][1], 0, 0, 0); }
	v_pk_mul_f32 v[34:35], v[34:35], v[176:177]
	v_pk_mul_f32 v[32:33], v[32:33], v[174:175]
	v_mfma_f32_16x16x32_bf16 v[108:111], v[140:143], v[212:215], v[216:219]
	v_mul_f32_e64 v2, v2, v176
	v_mul_f32_e64 v3, v3, v177
	ds_read_b64_tr_b16 v[210:211], v200 offset:1152
	ds_read_b64_tr_b16 v[208:209], v200
	v_pk_mul_f32 v[0:1], v[0:1], v[174:175]
	v_mfma_f32_16x16x32_bf16 v[104:107], v[136:139], v[212:215], v[220:223]
	ds_read_b64_tr_b16 v[212:213], v200 offset:32
	ds_read_b64_tr_b16 v[216:217], v200 offset:64
	s_nop 0
	ds_read_b64_tr_b16 v[220:221], v200 offset:96
	ds_read_b64_tr_b16 v[214:215], v200 offset:1184
	ds_read_b64_tr_b16 v[218:219], v200 offset:1216
	ds_read_b64_tr_b16 v[222:223], v200 offset:1248
	s_waitcnt lgkmcnt(8)
	v_pk_mul_f32 v[6:7], v[6:7], v[180:181]
	v_pk_mul_f32 v[4:5], v[4:5], v[178:179]
	ds_read_b128 v[174:177], v160 offset:128
	v_pk_mul_f32 v[10:11], v[10:11], v[180:181]
	v_pk_mul_f32 v[8:9], v[8:9], v[178:179]
	ds_read_b128 v[178:181], v160 offset:192
	s_waitcnt lgkmcnt(8)
	v_mfma_f32_16x16x32_bf16 v[32:35], v[208:211], v[148:151], v[32:35]
	s_waitcnt lgkmcnt(1)
	v_pk_mul_f32 v[14:15], v[14:15], v[176:177]
	v_pk_mul_f32 v[12:13], v[12:13], v[174:175]
	v_pk_mul_f32 v[18:19], v[18:19], v[176:177]
	v_pk_mul_f32 v[16:17], v[16:17], v[174:175]
	s_waitcnt lgkmcnt(0)
	v_pk_mul_f32 v[22:23], v[22:23], v[180:181]
	v_pk_mul_f32 v[20:21], v[20:21], v[178:179]
	ds_read_b128 v[174:177], v160 offset:256
	v_pk_mul_f32 v[26:27], v[26:27], v[180:181]
	v_pk_mul_f32 v[24:25], v[24:25], v[178:179]
	ds_read_b128 v[178:181], v160 offset:320
	v_mfma_f32_16x16x32_bf16 v[0:3], v[208:211], v[144:147], v[0:3]
	s_waitcnt lgkmcnt(1)
	v_pk_mul_f32 v[38:39], v[38:39], v[176:177]
	ds_read_b64_tr_b16 v[208:209], v200 offset:128
	ds_read_b64_tr_b16 v[210:211], v200 offset:1280
	v_pk_mul_f32 v[36:37], v[36:37], v[174:175]
	v_mfma_f32_16x16x32_bf16 v[4:7], v[212:215], v[148:151], v[4:7]
	v_mul_f32_e64 v30, v30, v176
	v_mul_f32_e64 v31, v31, v177
	v_pk_mul_f32 v[28:29], v[28:29], v[174:175]
	s_waitcnt lgkmcnt(2)
	v_pk_mul_f32 v[42:43], v[42:43], v[180:181]
	v_mfma_f32_16x16x32_bf16 v[8:11], v[212:215], v[144:147], v[8:11]
	v_mul_f32_e64 v40, v40, v178
	v_mul_f32_e64 v41, v41, v179
	v_pk_mul_f32 v[46:47], v[46:47], v[180:181]
	v_pk_mul_f32 v[44:45], v[44:45], v[178:179]
	v_mfma_f32_16x16x32_bf16 v[12:15], v[216:219], v[148:151], v[12:15]
	v_mfma_f32_16x16x32_bf16 v[16:19], v[216:219], v[144:147], v[16:19]
	v_mfma_f32_16x16x32_bf16 v[20:23], v[220:223], v[148:151], v[20:23]
	v_mfma_f32_16x16x32_bf16 v[24:27], v[220:223], v[144:147], v[24:27]
	ds_read_b64_tr_b16 v[212:213], v200 offset:160
	ds_read_b64_tr_b16 v[216:217], v200 offset:192
	ds_read_b64_tr_b16 v[220:221], v200 offset:224
	ds_read_b64_tr_b16 v[214:215], v200 offset:1312
	ds_read_b64_tr_b16 v[218:219], v200 offset:1344
	ds_read_b64_tr_b16 v[222:223], v200 offset:1376
	ds_read_b128 v[174:177], v160 offset:384
	ds_read_b128 v[178:181], v160 offset:448
	s_waitcnt lgkmcnt(8)
	v_mfma_f32_16x16x32_bf16 v[36:39], v[208:211], v[148:151], v[36:39]
	v_add_u32_e32 v160, s27, v192
	s_waitcnt lgkmcnt(1)
	v_pk_mul_f32 v[50:51], v[50:51], v[176:177]
	v_pk_mul_f32 v[48:49], v[48:49], v[174:175]
	v_pk_mul_f32 v[54:55], v[54:55], v[176:177]
	v_pk_mul_f32 v[52:53], v[52:53], v[174:175]
	s_waitcnt lgkmcnt(0)
	v_pk_mul_f32 v[58:59], v[58:59], v[180:181]
	v_pk_mul_f32 v[56:57], v[56:57], v[178:179]
	v_pk_mul_f32 v[62:63], v[62:63], v[180:181]
	v_pk_mul_f32 v[60:61], v[60:61], v[178:179]
	v_mfma_f32_16x16x32_bf16 v[28:31], v[208:211], v[144:147], v[28:31]
	v_mfma_f32_16x16x32_bf16 v[40:43], v[212:215], v[148:151], v[40:43]
	v_mfma_f32_16x16x32_bf16 v[44:47], v[212:215], v[144:147], v[44:47]
	v_mfma_f32_16x16x32_bf16 v[48:51], v[216:219], v[148:151], v[48:51]
	v_mfma_f32_16x16x32_bf16 v[52:55], v[216:219], v[144:147], v[52:55]
	v_mfma_f32_16x16x32_bf16 v[56:59], v[220:223], v[148:151], v[56:59]
	ds_read_b64_tr_b16 v[148:149], v200 offset:9216
	ds_read_b64_tr_b16 v[150:151], v200 offset:10368
	v_mfma_f32_16x16x32_bf16 v[60:63], v[220:223], v[144:147], v[60:63]
	ds_read_b64_tr_b16 v[144:145], v200 offset:9248
	ds_read_b64_tr_b16 v[174:175], v200 offset:9280
	ds_read_b64_tr_b16 v[178:179], v200 offset:9312
	ds_read_b64_tr_b16 v[146:147], v200 offset:10400
	ds_read_b64_tr_b16 v[176:177], v200 offset:10432
	ds_read_b64_tr_b16 v[180:181], v200 offset:10464
	s_waitcnt lgkmcnt(2)
; template <bool FULL>
; __device__ __forceinline__ void gla_pass(const Params& P, LAS unsigned char* lds, f32x4 (&S)[8][2], int bh, int c0, int L, bool dry) {
;     ...
;         if (FULL) {
; #pragma unroll
;             for (int vt = 0; vt < 2; ++vt)
; #pragma unroll
;                 for (int tt = 0; tt < 4; ++tt) zb[vt][tt] = *(const u32x2*)(PJ + T_ZB + ((size_t)bh * SEQ + n * 64 + 16 * tt + fr) * 256 + 32 * w + 16 * vt + 4 * g);
;         }
;         bf16x8 vf[2][2];
; #pragma unroll
;         for (int vt = 0; vt < 2; ++vt)
; #pragma unroll
;             for (int k2 = 0; k2 < 2; ++k2) vf[vt][k2] = trfrag(Lv, V_P, 32 * k2, (32 * w + 16 * vt) * 2, g, fr);
;         f32x4 o[2][4];
;         if (FULL) {
; #pragma unroll
;             for (int vt = 0; vt < 2; ++vt)
; #pragma unroll
;                 for (int tt = 0; tt < 4; ++tt) o[vt][tt] = (f32x4){0.f, 0.f, 0.f, 0.f};
; #pragma unroll
;             for (int k4 = 0; k4 < 4; ++k4) {
;                 const bf16x8 a0 = rowfrag(Lst, ST_P, 32 * w, 64 * k4, g, fr), a1 = rowfrag(Lst, ST_P, 32 * w + 16, 64 * k4, g, fr);
; #pragma unroll
;                 for (int tt = 0; tt < 4; ++tt) { const bf16x8 bq = rowfrag(Lqd, QD_P, 16 * tt, 64 * k4, g, fr);
;                     o[0][tt] = __builtin_amdgcn_mfma_f32_16x16x32_bf16(a0, bq, o[0][tt], 0, 0, 0); o[1][tt] = __builtin_amdgcn_mfma_f32_16x16x32_bf16(a1, bq, o[1][tt], 0, 0, 0); }
;             }
; #pragma unroll
;             for (int k2 = 0; k2 < 2; ++k2)
; #pragma unroll
;                 for (int tt = 0; tt < 4; ++tt) { const bf16x8 bp = rowfrag(Lp, P_P, 16 * tt, 64 * k2, g, fr);
;                     o[0][tt] = __builtin_amdgcn_mfma_f32_16x16x32_bf16(vf[0][k2], bp, o[0][tt], 0, 0, 0); o[1][tt] = __builtin_amdgcn_mfma_f32_16x16x32_bf16(vf[1][k2], bp, o[1][tt], 0, 0, 0); }
;         }
; #pragma unroll
;         for (int kt = 0; kt < 8; ++kt) { const f32x4 dv = *(const LAS f32x4*)(Ldec + 16 * kt + 4 * g); S[kt][0] = S[kt][0] * dv; S[kt][1] = S[kt][1] * dv; }
; #pragma unroll
;         for (int k2 = 0; k2 < 2; ++k2)
; #pragma unroll
;             for (int kt = 0; kt < 8; ++kt) { const bf16x8 ak = trfrag(Lks, KS_P, 32 * k2, 32 * kt, g, fr);
;                 S[kt][0] = __builtin_amdgcn_mfma_f32_16x16x32_bf16(ak, vf[0][k2], S[kt][0], 0, 0, 0); S[kt][1] = __builtin_amdgcn_mfma_f32_16x16x32_bf16(ak, vf[1][k2], S[kt][1], 0, 0, 0); }
;         if (FULL) {
; #pragma unroll
	v_mfma_f32_16x16x32_bf16 v[4:7], v[144:147], v[140:143], v[4:7]
	v_mfma_f32_16x16x32_bf16 v[8:11], v[144:147], v[136:139], v[8:11]
	ds_read_b64_tr_b16 v[144:145], v200 offset:9344
	ds_read_b64_tr_b16 v[146:147], v200 offset:10496
	ds_read_b64_tr_b16 v[208:209], v200 offset:9376
	ds_read_b64_tr_b16 v[212:213], v200 offset:9408
	ds_read_b64_tr_b16 v[216:217], v200 offset:9440
	ds_read_b64_tr_b16 v[210:211], v200 offset:10528
	ds_read_b64_tr_b16 v[214:215], v200 offset:10560
	ds_read_b64_tr_b16 v[218:219], v200 offset:10592
	v_mfma_f32_16x16x32_bf16 v[32:35], v[148:151], v[140:143], v[32:35]
	v_mfma_f32_16x16x32_bf16 v[0:3], v[148:151], v[136:139], v[0:3]
	v_lshlrev_b64 v[148:149], 9, v[160:161]
	v_lshl_add_u64 v[220:221], v[162:163], 0, v[148:149]
	v_or_b32_e32 v222, 0x2000, v148
	v_mfma_f32_16x16x32_bf16 v[116:119], v[140:143], v[224:227], v[228:231]
	v_mov_b32_e32 v223, v149
	v_lshl_add_u64 v[150:151], v[162:163], 0, v[222:223]
	v_mul_f32_e32 v160, v133, v133
	v_mfma_f32_16x16x32_bf16 v[112:115], v[136:139], v[224:227], v[112:115]
	v_or_b32_e32 v224, 0x4000, v148
	v_or_b32_e32 v148, 0x6000, v148
	v_mov_b32_e32 v225, v149
	s_waitcnt lgkmcnt(9)
	v_mfma_f32_16x16x32_bf16 v[12:15], v[174:177], v[140:143], v[12:15]
	v_lshl_add_u64 v[226:227], v[162:163], 0, v[224:225]
	v_fmac_f32_e32 v160, v132, v132
	v_mfma_f32_16x16x32_bf16 v[16:19], v[174:177], v[136:139], v[16:19]
	v_lshl_add_u64 v[174:175], v[162:163], 0, v[148:149]
	s_waitcnt lgkmcnt(6)
	v_mfma_f32_16x16x32_bf16 v[36:39], v[144:147], v[140:143], v[36:39]
	v_mfma_f32_16x16x32_bf16 v[28:31], v[144:147], v[136:139], v[28:31]
	v_lshl_add_u64 v[144:145], v[164:165], 0, v[222:223]
	v_lshl_add_u64 v[222:223], v[164:165], 0, v[148:149]
	v_mfma_f32_16x16x32_bf16 v[20:23], v[178:181], v[140:143], v[20:23]
	v_mfma_f32_16x16x32_bf16 v[24:27], v[178:181], v[136:139], v[24:27]
	global_load_dwordx2 v[180:181], v[220:221], off
	global_load_dwordx2 v[176:177], v[150:151], off
	s_nop 0
	global_load_dwordx2 v[150:151], v[226:227], off
	global_load_dwordx2 v[178:179], v[220:221], off offset:32
	v_lshl_add_u64 v[220:221], v[164:165], 0, v[224:225]
	global_load_dwordx2 v[146:147], v[174:175], off
	s_nop 0
	global_load_dwordx2 v[174:175], v[144:145], off
	global_load_dwordx2 v[148:149], v[220:221], off
	s_nop 0
	global_load_dwordx2 v[144:145], v[222:223], off
	s_waitcnt lgkmcnt(2)
	v_mfma_f32_16x16x32_bf16 v[40:43], v[208:211], v[140:143], v[40:43]
	v_mfma_f32_16x16x32_bf16 v[44:47], v[208:211], v[136:139], v[44:47]
	v_mul_f32_e32 v208, v135, v135
	v_fmac_f32_e32 v208, v134, v134
	v_add_f32_e32 v160, v160, v208
	v_mul_f32_e32 v208, v129, v129
	v_mul_f32_e32 v209, v131, v131
	v_fmac_f32_e32 v208, v128, v128
	v_fmac_f32_e32 v209, v130, v130
	v_add_f32_e32 v208, v208, v209
	s_waitcnt lgkmcnt(1)
	v_mfma_f32_16x16x32_bf16 v[48:51], v[212:215], v[140:143], v[48:51]
	s_waitcnt lgkmcnt(0)
	v_mfma_f32_16x16x32_bf16 v[56:59], v[216:219], v[140:143], v[56:59]
	v_add_f32_e32 v140, v160, v208
	v_mfma_f32_16x16x32_bf16 v[52:55], v[212:215], v[136:139], v[52:55]
	v_mfma_f32_16x16x32_bf16 v[60:63], v[216:219], v[136:139], v[60:63]
	v_mul_f32_e32 v246, v125, v125
	v_mul_f32_e32 v249, v127, v127
	v_fmac_f32_e32 v246, v124, v124
	v_fmac_f32_e32 v249, v126, v126
	v_add_f32_e32 v246, v246, v249
	v_mul_f32_e32 v249, v121, v121
	v_mul_f32_e32 v250, v123, v123
	v_fmac_f32_e32 v249, v120, v120
	v_fmac_f32_e32 v250, v122, v122
	v_add_f32_e32 v249, v249, v250
	v_add_f32_e32 v246, v246, v249
	v_mul_f32_e32 v247, v109, v109
	v_mul_f32_e32 v249, v111, v111
	v_fmac_f32_e32 v247, v108, v108
	v_fmac_f32_e32 v249, v110, v110
	v_add_f32_e32 v247, v247, v249
	v_mul_f32_e32 v249, v105, v105
	v_mul_f32_e32 v250, v107, v107
	v_fmac_f32_e32 v249, v104, v104
	v_fmac_f32_e32 v250, v106, v106
	v_add_f32_e32 v249, v249, v250
	v_add_f32_e32 v247, v247, v249
	v_mul_f32_e32 v248, v117, v117
	v_mul_f32_e32 v249, v119, v119
	v_fmac_f32_e32 v248, v116, v116
	v_fmac_f32_e32 v249, v118, v118
	v_add_f32_e32 v248, v248, v249
	v_mul_f32_e32 v249, v113, v113
	v_mul_f32_e32 v250, v115, v115
	v_fmac_f32_e32 v249, v112, v112
	v_fmac_f32_e32 v250, v114, v114
	v_add_f32_e32 v249, v249, v250
	v_add_f32_e32 v248, v248, v249
	ds_bpermute_b32 v141, v188, v140
	ds_bpermute_b32 v249, v188, v246
	ds_bpermute_b32 v250, v188, v247
	ds_bpermute_b32 v251, v188, v248
	s_waitcnt lgkmcnt(0)
	v_add_f32_e32 v140, v140, v141
	v_add_f32_e32 v246, v246, v249
	v_add_f32_e32 v247, v247, v250
	v_add_f32_e32 v248, v248, v251
	ds_bpermute_b32 v141, v189, v140
	ds_bpermute_b32 v249, v189, v246
	ds_bpermute_b32 v250, v189, v247
	ds_bpermute_b32 v251, v189, v248
	s_and_saveexec_b64 s[18:19], s[6:7]
	s_cbranch_execz .LBB0_711
	s_waitcnt lgkmcnt(0)
	v_add_f32_e32 v136, v140, v141
	ds_write_b32 v191, v136
	v_add_f32_e32 v136, v246, v249
	ds_write_b32 v191, v136 offset:512
	v_add_f32_e32 v136, v247, v250
	ds_write_b32 v191, v136 offset:1024
	v_add_f32_e32 v136, v248, v251
	ds_write_b32 v191, v136 offset:1536

; #define LAS __attribute__((address_space(3)))
; __global__ void __launch_bounds__(512, 2) k_mega(Params P) {
;     extern __shared__ __attribute__((aligned(16))) unsigned char shm[];
;     LAS unsigned char* lds = (LAS unsigned char*)shm;
	.amdhsa_kernel _Z6k_mega6Params
		.amdhsa_group_segment_fixed_size 0
		.amdhsa_private_segment_fixed_size 0
		.amdhsa_kernarg_size 392
		.amdhsa_user_sgpr_count 2
		.amdhsa_user_sgpr_dispatch_ptr 0
		.amdhsa_user_sgpr_queue_ptr 0
		.amdhsa_user_sgpr_kernarg_segment_ptr 1
		.amdhsa_user_sgpr_dispatch_id 0
		.amdhsa_user_sgpr_kernarg_preload_length 0
		.amdhsa_user_sgpr_kernarg_preload_offset 0
		.amdhsa_user_sgpr_private_segment_size 0
		.amdhsa_uses_dynamic_stack 0
		.amdhsa_enable_private_segment 0
		.amdhsa_system_sgpr_workgroup_id_x 1
		.amdhsa_system_sgpr_workgroup_id_y 0
		.amdhsa_system_sgpr_workgroup_id_z 0
		.amdhsa_system_sgpr_workgroup_info 0
		.amdhsa_system_vgpr_workitem_id 2
		.amdhsa_next_free_vgpr 256
		.amdhsa_next_free_sgpr 102
		.amdhsa_accum_offset 256
		.amdhsa_reserve_vcc 1
		.amdhsa_float_round_mode_32 0
		.amdhsa_float_round_mode_16_64 0
		.amdhsa_float_denorm_mode_32 3
		.amdhsa_float_denorm_mode_16_64 3
		.amdhsa_dx10_clamp 1
		.amdhsa_ieee_mode 1
		.amdhsa_fp16_overflow 0
		.amdhsa_tg_split 0
		.amdhsa_exception_fp_ieee_invalid_op 0
		.amdhsa_exception_fp_denorm_src 0
		.amdhsa_exception_fp_ieee_div_zero 0
		.amdhsa_exception_fp_ieee_overflow 0
		.amdhsa_exception_fp_ieee_underflow 0
		.amdhsa_exception_fp_ieee_inexact 0
		.amdhsa_exception_int_div_zero 0
	.end_amdhsa_kernel

; #define LAS __attribute__((address_space(3)))
; __global__ void __launch_bounds__(512, 2) k_mega(Params P) {
;     extern __shared__ __attribute__((aligned(16))) unsigned char shm[];
;     LAS unsigned char* lds = (LAS unsigned char*)shm;
amdhsa.kernels:
  - .agpr_count:     0
    .args:
      - .offset:         0
        .size:           136
        .value_kind:     by_value
      - .offset:         136
        .size:           4
        .value_kind:     hidden_block_count_x
      - .offset:         140
        .size:           4
        .value_kind:     hidden_block_count_y
      - .offset:         144
        .size:           4
        .value_kind:     hidden_block_count_z
      - .offset:         148
        .size:           2
        .value_kind:     hidden_group_size_x
      - .offset:         150
        .size:           2
        .value_kind:     hidden_group_size_y
      - .offset:         152
        .size:           2
        .value_kind:     hidden_group_size_z
      - .offset:         154
        .size:           2
        .value_kind:     hidden_remainder_x
      - .offset:         156
        .size:           2
        .value_kind:     hidden_remainder_y
      - .offset:         158
        .size:           2
        .value_kind:     hidden_remainder_z
      - .offset:         176
        .size:           8
        .value_kind:     hidden_global_offset_x
      - .offset:         184
        .size:           8
        .value_kind:     hidden_global_offset_y
      - .offset:         192
        .size:           8
        .value_kind:     hidden_global_offset_z
      - .offset:         200
        .size:           2
        .value_kind:     hidden_grid_dims
      - .offset:         224
        .size:           8
        .value_kind:     hidden_multigrid_sync_arg
      - .offset:         256
        .size:           4
        .value_kind:     hidden_dynamic_lds_size
    .group_segment_fixed_size: 0
    .kernarg_segment_align: 8
    .kernarg_segment_size: 392
    .language:       OpenCL C
    .language_version:
      - 2
      - 0
    .max_flat_workgroup_size: 512
    .name:           _Z6k_mega6Params
    .private_segment_fixed_size: 0
    .sgpr_count:     108
    .sgpr_spill_count: 10
    .symbol:         _Z6k_mega6Params.kd
    .uniform_work_group_size: 1
    .uses_dynamic_stack: false
    .vgpr_count:     256
    .vgpr_spill_count: 0
    .wavefront_size: 64
